# retention tile loop: back edge rotated, next-tile K read addresses computed before the end-of-tile barrier
# baseline (speedup 1.0000x reference)
.LBB0_865:
	s_and_b32 s49, s48, 1
	s_cmp_gt_i32 s45, s16
	s_cbranch_scc1 .Lt_skipdma
	s_mul_i32 s4, s49, 0x8400
	v_add_u32_e32 v8, s4, v195
	v_xor_b32_e32 v246, 64, v8
	v_xor_b32_e32 v247, 0x80, v8
	v_xor_b32_e32 v248, 0xc0, v8
	s_branch .Lr_reads

.LBB0_864:
	s_add_i32 s48, s48, 1
	s_add_i32 s45, s45, 64
	v_subrev_u32_e32 v196, 64, v196
	s_and_b32 s49, s48, 1
	s_mul_i32 s4, s49, 0x8400
	v_add_u32_e32 v8, s4, v195
	v_xor_b32_e32 v246, 64, v8
	v_xor_b32_e32 v247, 0x80, v8
	v_xor_b32_e32 v248, 0xc0, v8
	s_cmp_eq_u32 s17, s48
	s_waitcnt vmcnt(0) lgkmcnt(0)
	s_barrier
	s_cbranch_scc1 .LBB0_870
	s_cmp_gt_i32 s45, s16
	s_cbranch_scc1 .Lt_skipdma
.Lr_reads:
	ds_read_b128 v[0:3], v8
	ds_read_b128 v[4:7], v8 offset:8192
	ds_read_b128 v[174:177], v8 offset:16384
	ds_read_b128 v[198:201], v8 offset:24576
	ds_read_b128 v[202:205], v246
	ds_read_b128 v[206:209], v246 offset:8192
	ds_read_b128 v[210:213], v246 offset:16384
	ds_read_b128 v[214:217], v246 offset:24576
	ds_read_b128 v[218:221], v247
	ds_read_b128 v[226:229], v247 offset:8192
	ds_read_b128 v[230:233], v247 offset:16384
	ds_read_b128 v[234:237], v247 offset:24576
	ds_read_b128 v[238:241], v248
	ds_read_b128 v[242:245], v248 offset:8192
	s_mul_i32 s5, s49, 0x8800
	v_add_u32_e32 v115, s5, v173
	v_xor_b32_e32 v108, 0x20, v115
	v_xor_b32_e32 v109, 0x40, v115
	v_xor_b32_e32 v110, 0x60, v115
	v_xor_b32_e32 v111, 0x80, v115
	v_xor_b32_e32 v112, 0xa0, v115
	v_xor_b32_e32 v113, 0xc0, v115
	v_xor_b32_e32 v114, 0xe0, v115
	s_add_i32 s4, s45, 63
	s_cmp_le_u32 s4, s9
	s_waitcnt lgkmcnt(13)
	v_mfma_f32_16x16x32_bf16 v[150:153], v[0:3], v[102:105], 0
	ds_read_b128 v[0:3], v248 offset:16384
	s_waitcnt lgkmcnt(13)
	v_mfma_f32_16x16x32_bf16 v[146:149], v[4:7], v[102:105], 0
	ds_read_b128 v[4:7], v248 offset:24576
	s_waitcnt lgkmcnt(13)
	v_mfma_f32_16x16x32_bf16 v[142:145], v[174:177], v[102:105], 0
	ds_read_b128 v[174:177], v8 offset:256
	s_waitcnt lgkmcnt(13)
	v_mfma_f32_16x16x32_bf16 v[138:141], v[198:201], v[102:105], 0
	ds_read_b128 v[198:201], v8 offset:8448
	s_waitcnt lgkmcnt(13)
	v_mfma_f32_16x16x32_bf16 v[150:153], v[202:205], v[98:101], v[150:153]
	ds_read_b128 v[202:205], v8 offset:16640
	s_waitcnt lgkmcnt(13)
	v_mfma_f32_16x16x32_bf16 v[146:149], v[206:209], v[98:101], v[146:149]
	ds_read_b128 v[206:209], v8 offset:24832
	s_waitcnt lgkmcnt(13)
	v_mfma_f32_16x16x32_bf16 v[142:145], v[210:213], v[98:101], v[142:145]
	ds_read_b128 v[210:213], v246 offset:256
	s_waitcnt lgkmcnt(13)
	v_mfma_f32_16x16x32_bf16 v[138:141], v[214:217], v[98:101], v[138:141]
	ds_read_b128 v[214:217], v246 offset:8448
	s_waitcnt lgkmcnt(13)
	v_mfma_f32_16x16x32_bf16 v[150:153], v[218:221], v[94:97], v[150:153]
	ds_read_b128 v[218:221], v246 offset:16640
	s_waitcnt lgkmcnt(13)
	v_mfma_f32_16x16x32_bf16 v[146:149], v[226:229], v[94:97], v[146:149]
	ds_read_b128 v[226:229], v246 offset:24832
	s_waitcnt lgkmcnt(13)
	v_mfma_f32_16x16x32_bf16 v[142:145], v[230:233], v[94:97], v[142:145]
	ds_read_b128 v[230:233], v247 offset:256
	s_waitcnt lgkmcnt(13)
	v_mfma_f32_16x16x32_bf16 v[138:141], v[234:237], v[94:97], v[138:141]
	ds_read_b128 v[234:237], v247 offset:8448
	s_waitcnt lgkmcnt(13)
	v_mfma_f32_16x16x32_bf16 v[150:153], v[238:241], v[90:93], v[150:153]
	ds_read_b128 v[238:241], v247 offset:16640
	s_waitcnt lgkmcnt(13)
	v_mfma_f32_16x16x32_bf16 v[146:149], v[242:245], v[90:93], v[146:149]
	ds_read_b128 v[242:245], v247 offset:24832
	s_waitcnt lgkmcnt(13)
	v_mfma_f32_16x16x32_bf16 v[142:145], v[0:3], v[90:93], v[142:145]
	ds_read_b128 v[0:3], v248 offset:256
	s_waitcnt lgkmcnt(13)
	v_mfma_f32_16x16x32_bf16 v[138:141], v[4:7], v[90:93], v[138:141]
	ds_read_b128 v[4:7], v248 offset:8448
	s_waitcnt lgkmcnt(13)
	v_mfma_f32_16x16x32_bf16 v[150:153], v[174:177], v[86:89], v[150:153]
	ds_read_b128 v[174:177], v248 offset:16640
	s_waitcnt lgkmcnt(13)
	v_mfma_f32_16x16x32_bf16 v[146:149], v[198:201], v[86:89], v[146:149]
	ds_read_b128 v[198:201], v248 offset:24832
	s_waitcnt lgkmcnt(13)
	v_mfma_f32_16x16x32_bf16 v[142:145], v[202:205], v[86:89], v[142:145]
	ds_read_b64_tr_b16 v[116:117], v115
	ds_read_b64_tr_b16 v[118:119], v115 offset:8192
	s_waitcnt lgkmcnt(14)
	v_mfma_f32_16x16x32_bf16 v[138:141], v[206:209], v[86:89], v[138:141]
	ds_read_b64_tr_b16 v[120:121], v108
	s_waitcnt lgkmcnt(14)
	v_mfma_f32_16x16x32_bf16 v[150:153], v[210:213], v[82:85], v[150:153]
	ds_read_b64_tr_b16 v[122:123], v108 offset:8192
	s_waitcnt lgkmcnt(14)
	v_mfma_f32_16x16x32_bf16 v[146:149], v[214:217], v[82:85], v[146:149]
	ds_read_b64_tr_b16 v[124:125], v109
	s_waitcnt lgkmcnt(14)
	v_mfma_f32_16x16x32_bf16 v[142:145], v[218:221], v[82:85], v[142:145]
	ds_read_b64_tr_b16 v[126:127], v109 offset:8192
	s_waitcnt lgkmcnt(14)
	v_mfma_f32_16x16x32_bf16 v[138:141], v[226:229], v[82:85], v[138:141]
	ds_read_b64_tr_b16 v[128:129], v110
	s_waitcnt lgkmcnt(14)
	v_mfma_f32_16x16x32_bf16 v[150:153], v[230:233], v[78:81], v[150:153]
	ds_read_b64_tr_b16 v[130:131], v110 offset:8192
	s_waitcnt lgkmcnt(14)
	v_mfma_f32_16x16x32_bf16 v[146:149], v[234:237], v[78:81], v[146:149]
	ds_read_b64_tr_b16 v[210:211], v111
	s_waitcnt lgkmcnt(14)
	v_mfma_f32_16x16x32_bf16 v[142:145], v[238:241], v[78:81], v[142:145]
	ds_read_b64_tr_b16 v[212:213], v111 offset:8192
	s_waitcnt lgkmcnt(14)
	v_mfma_f32_16x16x32_bf16 v[138:141], v[242:245], v[78:81], v[138:141]
	ds_read_b64_tr_b16 v[202:203], v112
	s_waitcnt lgkmcnt(14)
	v_mfma_f32_16x16x32_bf16 v[150:153], v[0:3], v[74:77], v[150:153]
	ds_read_b64_tr_b16 v[204:205], v112 offset:8192
	s_waitcnt lgkmcnt(14)
	v_mfma_f32_16x16x32_bf16 v[146:149], v[4:7], v[74:77], v[146:149]
	ds_read_b64_tr_b16 v[206:207], v113
	s_waitcnt lgkmcnt(14)
	v_mfma_f32_16x16x32_bf16 v[142:145], v[174:177], v[74:77], v[142:145]
	ds_read_b64_tr_b16 v[208:209], v113 offset:8192
	s_waitcnt lgkmcnt(14)
	v_mfma_f32_16x16x32_bf16 v[138:141], v[198:201], v[74:77], v[138:141]
	s_lshl_b32 s4, s45, 14
	s_add_i32 s4, s4, 0x100000
	v_readlane_b32 s5, v254, 60
	s_lshl_b32 s5, s5, 10
	s_cmp_eq_u32 s49, 0
	s_cselect_b32 m0, 0x8400, 0
	s_add_i32 m0, m0, s5
	v_add_u32_e32 v0, s4, v106
	v_add_u32_e32 v4, s4, v107
	global_load_lds_dwordx4 v0, s[24:25]
	s_add_i32 m0, m0, 0x2000
	s_add_i32 s4, s4, 0x40000
	v_add_u32_e32 v1, s4, v106
	v_add_u32_e32 v5, s4, v107
	global_load_lds_dwordx4 v1, s[24:25]
	s_add_i32 m0, m0, 0x2000
	s_add_i32 s4, s4, 0x40000
	v_add_u32_e32 v2, s4, v106
	v_add_u32_e32 v6, s4, v107
	global_load_lds_dwordx4 v2, s[24:25]
	s_add_i32 m0, m0, 0x2000
	s_add_i32 s4, s4, 0x40000
	v_add_u32_e32 v3, s4, v106
	v_add_u32_e32 v7, s4, v107
	global_load_lds_dwordx4 v3, s[24:25]
	s_cmp_eq_u32 s49, 0
	s_cselect_b32 m0, 0x8800, 0
	s_add_i32 m0, m0, s5
	s_add_i32 m0, m0, 0x10800
	s_nop 0
	global_load_lds_dwordx4 v4, s[26:27]
	s_add_i32 m0, m0, 0x2000
	s_nop 0
	global_load_lds_dwordx4 v5, s[26:27]
	s_add_i32 m0, m0, 0x2000
	s_nop 0
	global_load_lds_dwordx4 v6, s[26:27]
	s_add_i32 m0, m0, 0x2000
	s_nop 0
	global_load_lds_dwordx4 v7, s[26:27]
	s_add_i32 s4, s45, 63
	s_cmp_le_u32 s4, s9
	s_mov_b64 s[4:5], -1
	s_cbranch_scc0 .LBB0_868
	v_cvt_f32_i32_e32 v0, v196
	s_mov_b64 s[4:5], 0
	v_mul_f32_e32 v0, v178, v0
	v_exp_f32_e32 v8, v0
	s_nop 0
	v_mul_f32_e32 v0, s40, v8
	v_pk_mul_f32 v[2:3], s[40:41], v[0:1] op_sel_hi:[1,0]
	v_pk_mul_f32 v[0:1], s[42:43], v[0:1] op_sel_hi:[1,0]
	v_pk_mul_f32 v[2:3], v[2:3], v[150:151]
	v_pk_mul_f32 v[4:5], v[0:1], v[152:153]
	v_cvt_pk_bf16_f32 v0, v2, v3
	v_mul_f32_e32 v2, s44, v8
	v_cvt_pk_bf16_f32 v1, v4, v5
	v_pk_mul_f32 v[4:5], s[40:41], v[2:3] op_sel_hi:[1,0]
	v_pk_mul_f32 v[2:3], s[42:43], v[2:3] op_sel_hi:[1,0]
	v_pk_mul_f32 v[4:5], v[4:5], v[146:147]
	v_pk_mul_f32 v[6:7], v[2:3], v[148:149]
	v_cvt_pk_bf16_f32 v2, v4, v5
	v_mul_f32_e32 v4, s37, v8
	v_cvt_pk_bf16_f32 v3, v6, v7
	v_pk_mul_f32 v[6:7], s[40:41], v[4:5] op_sel_hi:[1,0]
	v_pk_mul_f32 v[4:5], s[42:43], v[4:5] op_sel_hi:[1,0]
	v_pk_mul_f32 v[6:7], v[6:7], v[142:143]
	v_pk_mul_f32 v[154:155], v[4:5], v[144:145]
	v_cvt_pk_bf16_f32 v4, v6, v7
	v_mul_f32_e32 v6, s36, v8
	v_cvt_pk_bf16_f32 v5, v154, v155
	v_pk_mul_f32 v[154:155], s[40:41], v[6:7] op_sel_hi:[1,0]
	v_pk_mul_f32 v[6:7], s[42:43], v[6:7] op_sel_hi:[1,0]
	v_pk_mul_f32 v[174:175], v[154:155], v[138:139]
	v_pk_mul_f32 v[176:177], v[6:7], v[140:141]
